# v55 + work redistribution: 288 of 544 hyena filter tiles moved from the k0 phase into the idle third round of the even in-proj GEMM (WGs 168..255)
# baseline (speedup 1.0000x reference)
.LBB0_475:
	s_waitcnt vmcnt(0)
	v_readlane_b32 s28, v255, 4
	v_readlane_b32 s36, v255, 6
	v_readlane_b32 s70, v255, 8
	v_readlane_b32 s74, v255, 10
	v_readlane_b32 s29, v255, 5
	v_readlane_b32 s37, v255, 7
	v_readlane_b32 s71, v255, 9
	v_readlane_b32 s75, v255, 11
	s_mov_b32 s34, 0xc200000
	s_barrier
	s_cmp_eq_u32 s56, 0x100
	s_cbranch_scc0 .LBB0_476
	s_cmp_lt_u32 s96, 0xa8
	s_cbranch_scc1 .LBB0_476
	s_mov_b64 s[0:1], s[72:73]
	s_load_dwordx2 s[64:65], s[72:73], 0x120
	s_add_i32 s101, s96, 0x58
	s_movk_i32 s98, 0x58
	s_movk_i32 s99, 0x21f
	s_waitcnt lgkmcnt(0)
	s_branch .Lkt_entry
	s_nop 0

.LBB0_562:
	v_readlane_b32 s2, v253, 16
	v_readlane_b32 s6, v255, 22
	v_readlane_b32 s3, v253, 17
	v_readlane_b32 s7, v255, 23
	s_or_b64 s[2:3], s[6:7], s[2:3]
	s_and_b64 vcc, exec, s[2:3]
	s_cbranch_vccnz .LBB0_567
	s_mov_b32 s101, s96
	s_mov_b32 s98, s56
	s_movk_i32 s99, 0x21f
	s_cmp_eq_u32 s56, 0x100
	s_cbranch_scc0 .Lkt_entry
	s_movk_i32 s99, 0xff
	s_nop 0
.Lkt_entry:
	v_readlane_b32 s8, v255, 29
	v_readlane_b32 s9, v255, 30
	s_mul_i32 s7, s8, 0x110000
	s_lshl_b64 s[2:3], s[8:9], 19
	s_waitcnt lgkmcnt(0)
	s_lshl_b32 s10, s8, 11
	s_mul_hi_i32 s6, s8, 0x110000
	s_add_u32 s7, s64, s7
	s_addc_u32 s8, s65, s6
	s_add_u32 s6, s7, 0x100000
	s_addc_u32 s7, s8, 0
	s_add_u32 s11, s64, 0x11c00000
	s_addc_u32 s12, s65, 0
	s_mov_b32 s13, s101

.LBB0_565:
	v_add_u32_e32 v37, s14, v36
	ds_read_b128 v[38:41], v35
	ds_read_b128 v[42:45], v37
	ds_read_b128 v[46:49], v37 offset:16
	s_addk_i32 s14, 0x800
	s_cmpk_lg_u32 s14, 0x8000
	s_waitcnt lgkmcnt(1)
	v_pk_fma_f32 v[32:33], v[40:41], v[42:43], v[32:33] op_sel_hi:[1,0,1]
	v_pk_fma_f32 v[30:31], v[38:39], v[42:43], v[30:31] op_sel_hi:[1,0,1]
	v_pk_fma_f32 v[28:29], v[40:41], v[42:43], v[28:29] op_sel:[0,1,0]
	v_pk_fma_f32 v[26:27], v[38:39], v[42:43], v[26:27] op_sel:[0,1,0]
	v_mov_b32_e32 v42, v45
	s_waitcnt lgkmcnt(0)
	v_pk_fma_f32 v[50:51], v[38:39], v[48:49], v[6:7] op_sel_hi:[1,0,1]
	v_mov_b32_e32 v6, v49
	v_pk_fma_f32 v[24:25], v[40:41], v[44:45], v[24:25] op_sel_hi:[1,0,1]
	v_pk_fma_f32 v[22:23], v[38:39], v[44:45], v[22:23] op_sel_hi:[1,0,1]
	v_pk_fma_f32 v[20:21], v[40:41], v[42:43], v[20:21] op_sel_hi:[1,0,1]
	v_pk_fma_f32 v[18:19], v[38:39], v[42:43], v[18:19] op_sel_hi:[1,0,1]
	v_pk_fma_f32 v[16:17], v[40:41], v[46:47], v[16:17] op_sel_hi:[1,0,1]
	v_pk_fma_f32 v[14:15], v[38:39], v[46:47], v[14:15] op_sel_hi:[1,0,1]
	v_pk_fma_f32 v[42:43], v[40:41], v[46:47], v[12:13] op_sel:[0,1,0]
	v_pk_fma_f32 v[44:45], v[38:39], v[46:47], v[10:11] op_sel:[0,1,0]
	v_pk_fma_f32 v[46:47], v[40:41], v[48:49], v[8:9] op_sel_hi:[1,0,1]
	v_pk_fma_f32 v[40:41], v[40:41], v[6:7], v[4:5] op_sel_hi:[1,0,1]
	v_pk_fma_f32 v[38:39], v[38:39], v[6:7], v[2:3] op_sel_hi:[1,0,1]
	ds_read_b128 v[2:5], v35 offset:528
	ds_read_b128 v[6:9], v37 offset:512
	ds_read_b128 v[10:13], v37 offset:528
	s_waitcnt lgkmcnt(1)
	v_pk_fma_f32 v[32:33], v[4:5], v[6:7], v[32:33] op_sel_hi:[1,0,1]
	v_pk_fma_f32 v[30:31], v[2:3], v[6:7], v[30:31] op_sel_hi:[1,0,1]
	v_pk_fma_f32 v[28:29], v[4:5], v[6:7], v[28:29] op_sel:[0,1,0]
	v_pk_fma_f32 v[26:27], v[2:3], v[6:7], v[26:27] op_sel:[0,1,0]
	v_mov_b32_e32 v6, v9
	v_pk_fma_f32 v[20:21], v[4:5], v[6:7], v[20:21] op_sel_hi:[1,0,1]
	v_pk_fma_f32 v[18:19], v[2:3], v[6:7], v[18:19] op_sel_hi:[1,0,1]
	s_waitcnt lgkmcnt(0)
	v_mov_b32_e32 v6, v13
	v_pk_fma_f32 v[24:25], v[4:5], v[8:9], v[24:25] op_sel_hi:[1,0,1]
	v_pk_fma_f32 v[22:23], v[2:3], v[8:9], v[22:23] op_sel_hi:[1,0,1]
	v_pk_fma_f32 v[16:17], v[4:5], v[10:11], v[16:17] op_sel_hi:[1,0,1]
	v_pk_fma_f32 v[14:15], v[2:3], v[10:11], v[14:15] op_sel_hi:[1,0,1]
	v_pk_fma_f32 v[42:43], v[4:5], v[10:11], v[42:43] op_sel:[0,1,0]
	v_pk_fma_f32 v[44:45], v[2:3], v[10:11], v[44:45] op_sel:[0,1,0]
	v_pk_fma_f32 v[46:47], v[4:5], v[12:13], v[46:47] op_sel_hi:[1,0,1]
	v_pk_fma_f32 v[48:49], v[2:3], v[12:13], v[50:51] op_sel_hi:[1,0,1]
	v_pk_fma_f32 v[40:41], v[4:5], v[6:7], v[40:41] op_sel_hi:[1,0,1]
	v_pk_fma_f32 v[38:39], v[2:3], v[6:7], v[38:39] op_sel_hi:[1,0,1]
	ds_read_b128 v[2:5], v35 offset:1056
	ds_read_b128 v[6:9], v37 offset:1024
	ds_read_b128 v[10:13], v37 offset:1040
	s_waitcnt lgkmcnt(1)
	v_pk_fma_f32 v[32:33], v[4:5], v[6:7], v[32:33] op_sel_hi:[1,0,1]
	v_pk_fma_f32 v[30:31], v[2:3], v[6:7], v[30:31] op_sel_hi:[1,0,1]
	v_pk_fma_f32 v[28:29], v[4:5], v[6:7], v[28:29] op_sel:[0,1,0]
	v_pk_fma_f32 v[26:27], v[2:3], v[6:7], v[26:27] op_sel:[0,1,0]
	v_mov_b32_e32 v6, v9
	v_pk_fma_f32 v[20:21], v[4:5], v[6:7], v[20:21] op_sel_hi:[1,0,1]
	v_pk_fma_f32 v[18:19], v[2:3], v[6:7], v[18:19] op_sel_hi:[1,0,1]
	s_waitcnt lgkmcnt(0)
	v_mov_b32_e32 v6, v13
	v_pk_fma_f32 v[24:25], v[4:5], v[8:9], v[24:25] op_sel_hi:[1,0,1]
	v_pk_fma_f32 v[22:23], v[2:3], v[8:9], v[22:23] op_sel_hi:[1,0,1]
	v_pk_fma_f32 v[16:17], v[4:5], v[10:11], v[16:17] op_sel_hi:[1,0,1]
	v_pk_fma_f32 v[14:15], v[2:3], v[10:11], v[14:15] op_sel_hi:[1,0,1]
	v_pk_fma_f32 v[42:43], v[4:5], v[10:11], v[42:43] op_sel:[0,1,0]
	v_pk_fma_f32 v[10:11], v[2:3], v[10:11], v[44:45] op_sel:[0,1,0]
	v_pk_fma_f32 v[44:45], v[4:5], v[12:13], v[46:47] op_sel_hi:[1,0,1]
	v_pk_fma_f32 v[46:47], v[2:3], v[12:13], v[48:49] op_sel_hi:[1,0,1]
	v_pk_fma_f32 v[48:49], v[4:5], v[6:7], v[40:41] op_sel_hi:[1,0,1]
	v_pk_fma_f32 v[50:51], v[2:3], v[6:7], v[38:39] op_sel_hi:[1,0,1]
	ds_read_b128 v[2:5], v35 offset:1584
	ds_read_b128 v[6:9], v37 offset:1536
	ds_read_b128 v[38:41], v37 offset:1552
	v_add_u32_e32 v35, 0x840, v35
	s_waitcnt lgkmcnt(1)
	v_pk_fma_f32 v[32:33], v[4:5], v[6:7], v[32:33] op_sel_hi:[1,0,1]
	v_pk_fma_f32 v[30:31], v[2:3], v[6:7], v[30:31] op_sel_hi:[1,0,1]
	v_pk_fma_f32 v[28:29], v[4:5], v[6:7], v[28:29] op_sel:[0,1,0]
	v_pk_fma_f32 v[26:27], v[2:3], v[6:7], v[26:27] op_sel:[0,1,0]
	v_mov_b32_e32 v6, v9
	s_waitcnt lgkmcnt(0)
	v_pk_fma_f32 v[16:17], v[4:5], v[38:39], v[16:17] op_sel_hi:[1,0,1]
	v_pk_fma_f32 v[14:15], v[2:3], v[38:39], v[14:15] op_sel_hi:[1,0,1]
	v_pk_fma_f32 v[12:13], v[4:5], v[38:39], v[42:43] op_sel:[0,1,0]
	v_pk_fma_f32 v[10:11], v[2:3], v[38:39], v[10:11] op_sel:[0,1,0]
	v_mov_b32_e32 v38, v41
	v_pk_fma_f32 v[24:25], v[4:5], v[8:9], v[24:25] op_sel_hi:[1,0,1]
	v_pk_fma_f32 v[22:23], v[2:3], v[8:9], v[22:23] op_sel_hi:[1,0,1]
	v_pk_fma_f32 v[20:21], v[4:5], v[6:7], v[20:21] op_sel_hi:[1,0,1]
	v_pk_fma_f32 v[18:19], v[2:3], v[6:7], v[18:19] op_sel_hi:[1,0,1]
	v_pk_fma_f32 v[8:9], v[4:5], v[40:41], v[44:45] op_sel_hi:[1,0,1]
	v_pk_fma_f32 v[6:7], v[2:3], v[40:41], v[46:47] op_sel_hi:[1,0,1]
	v_pk_fma_f32 v[4:5], v[4:5], v[38:39], v[48:49] op_sel_hi:[1,0,1]
	v_pk_fma_f32 v[2:3], v[2:3], v[38:39], v[50:51] op_sel_hi:[1,0,1]
	s_cbranch_scc1 .LBB0_565
	v_ashrrev_i32_e32 v34, 2, v34
	s_load_dwordx2 s[14:15], s[0:1], 0x88
	v_and_b32_e32 v34, -8, v34
	v_add_u32_e32 v37, s9, v34
	v_add_u32_e32 v34, s10, v37
	v_ashrrev_i32_e32 v35, 31, v34
	s_waitcnt lgkmcnt(0)
	v_lshl_add_u64 v[34:35], v[34:35], 2, s[14:15]
	global_load_dword v36, v[34:35], off
	global_load_dword v52, v[34:35], off offset:4
	global_load_dword v54, v[34:35], off offset:8
	global_load_dword v56, v[34:35], off offset:12
	global_load_dword v58, v[34:35], off offset:16
	global_load_dword v60, v[34:35], off offset:20
	global_load_dword v62, v[34:35], off offset:24
	global_load_dword v64, v[34:35], off offset:28
	s_ashr_i32 s9, s8, 31
	s_lshl_b64 s[8:9], s[8:9], 2
	s_add_u32 s8, s11, s8
	v_lshlrev_b32_e32 v0, 4, v0
	s_addc_u32 s9, s12, s9
	v_lshl_add_u64 v[38:39], s[8:9], 0, v[0:1]
	v_mad_i64_i32 v[40:41], s[8:9], v37, s61, v[38:39]
	s_add_i32 s13, s13, s98
	s_cmp_gt_i32 s13, s99
	s_waitcnt vmcnt(0)
	v_pk_add_f32 v[32:33], v[32:33], v[36:37] op_sel_hi:[1,0]
	v_pk_add_f32 v[30:31], v[30:31], v[36:37] op_sel_hi:[1,0]
	global_store_dwordx4 v[40:41], v[30:33], off
	s_nop 1
	v_pk_add_f32 v[28:29], v[28:29], v[52:53] op_sel_hi:[1,0]
	v_or_b32_e32 v30, 1, v37
	v_mad_i64_i32 v[30:31], s[8:9], v30, s61, v[38:39]
	v_pk_add_f32 v[26:27], v[26:27], v[52:53] op_sel_hi:[1,0]
	global_store_dwordx4 v[30:31], v[26:29], off
	s_nop 1
	v_pk_add_f32 v[24:25], v[24:25], v[54:55] op_sel_hi:[1,0]
	v_or_b32_e32 v26, 2, v37
	v_mad_i64_i32 v[26:27], s[8:9], v26, s61, v[38:39]
	v_pk_add_f32 v[22:23], v[22:23], v[54:55] op_sel_hi:[1,0]
	global_store_dwordx4 v[26:27], v[22:25], off
	s_nop 1
	v_pk_add_f32 v[20:21], v[20:21], v[56:57] op_sel_hi:[1,0]
	v_or_b32_e32 v22, 3, v37
	v_mad_i64_i32 v[22:23], s[8:9], v22, s61, v[38:39]
	v_pk_add_f32 v[18:19], v[18:19], v[56:57] op_sel_hi:[1,0]
	global_store_dwordx4 v[22:23], v[18:21], off
	s_nop 1
	v_pk_add_f32 v[16:17], v[16:17], v[58:59] op_sel_hi:[1,0]
	v_or_b32_e32 v18, 4, v37
	v_mad_i64_i32 v[18:19], s[8:9], v18, s61, v[38:39]
	v_pk_add_f32 v[14:15], v[14:15], v[58:59] op_sel_hi:[1,0]
	global_store_dwordx4 v[18:19], v[14:17], off
	s_nop 1
	v_pk_add_f32 v[12:13], v[12:13], v[60:61] op_sel_hi:[1,0]
	v_or_b32_e32 v14, 5, v37
	v_mad_i64_i32 v[14:15], s[8:9], v14, s61, v[38:39]
	v_pk_add_f32 v[10:11], v[10:11], v[60:61] op_sel_hi:[1,0]
	global_store_dwordx4 v[14:15], v[10:13], off
	s_nop 1
	v_pk_add_f32 v[8:9], v[8:9], v[62:63] op_sel_hi:[1,0]
	v_or_b32_e32 v10, 6, v37
	v_mad_i64_i32 v[10:11], s[8:9], v10, s61, v[38:39]
	v_pk_add_f32 v[6:7], v[6:7], v[62:63] op_sel_hi:[1,0]
	global_store_dwordx4 v[10:11], v[6:9], off
	s_nop 1
	v_pk_add_f32 v[4:5], v[4:5], v[64:65] op_sel_hi:[1,0]
	v_or_b32_e32 v6, 7, v37
	v_mad_i64_i32 v[6:7], s[8:9], v6, s61, v[38:39]
	v_pk_add_f32 v[2:3], v[2:3], v[64:65] op_sel_hi:[1,0]
	global_store_dwordx4 v[6:7], v[2:5], off
	s_nop 1
	s_barrier
	s_cbranch_scc0 .LBB0_564
